# combo18 + E61: the leading wave group (waves 0..3, one barrier ahead) runs its own copy of the in-proj GEMM main loop whose LDS-DMA retire wait sits before the second barrier of each phase instead of
# speedup vs baseline: 1.0013x; 1.0013x over previous
.LBB0_276:
	s_ashr_i32 s45, s44, 31
	s_lshl_b64 s[12:13], s[44:45], 19
	s_add_u32 s46, s14, s12
	s_addc_u32 s47, s15, s13
	s_and_b64 s[12:13], s[38:39], exec
	s_cselect_b32 s34, s47, s9
	s_cselect_b32 s35, s46, s8
	s_ashr_i32 s43, s42, 31
	s_lshl_b64 s[12:13], s[42:43], 19
	s_add_u32 s48, s4, s12
	s_addc_u32 s49, s5, s13
	s_and_b64 s[12:13], s[38:39], exec
	s_cselect_b32 s43, s49, s11
	s_cselect_b32 s45, s48, s10
	s_add_u32 s8, s8, 0x40080
	s_addc_u32 s9, s9, 0
	s_add_u32 s50, s10, 0x100
	v_mov_b32_e32 v0, 0
	s_addc_u32 s51, s11, 0
	s_mov_b32 s52, -2
	v_mov_b32_e32 v1, v0
	v_mov_b32_e32 v2, v0
	v_mov_b32_e32 v3, v0
	v_mov_b32_e32 v4, v0
	v_mov_b32_e32 v5, v0
	v_mov_b32_e32 v6, v0
	v_mov_b32_e32 v7, v0
	v_mov_b32_e32 v8, v0
	v_mov_b32_e32 v9, v0
	v_mov_b32_e32 v10, v0
	v_mov_b32_e32 v11, v0
	v_mov_b32_e32 v12, v0
	v_mov_b32_e32 v13, v0
	v_mov_b32_e32 v14, v0
	v_mov_b32_e32 v15, v0
	v_mov_b32_e32 v16, v0
	v_mov_b32_e32 v17, v0
	v_mov_b32_e32 v18, v0
	v_mov_b32_e32 v19, v0
	v_mov_b32_e32 v20, v0
	v_mov_b32_e32 v21, v0
	v_mov_b32_e32 v22, v0
	v_mov_b32_e32 v23, v0
	v_mov_b32_e32 v24, v0
	v_mov_b32_e32 v25, v0
	v_mov_b32_e32 v26, v0
	v_mov_b32_e32 v27, v0
	v_mov_b32_e32 v28, v0
	v_mov_b32_e32 v29, v0
	v_mov_b32_e32 v30, v0
	v_mov_b32_e32 v31, v0
	v_mov_b32_e32 v56, v0
	v_mov_b32_e32 v57, v0
	v_mov_b32_e32 v58, v0
	v_mov_b32_e32 v59, v0
	v_mov_b32_e32 v60, v0
	v_mov_b32_e32 v61, v0
	v_mov_b32_e32 v62, v0
	v_mov_b32_e32 v63, v0
	v_mov_b32_e32 v72, v0
	v_mov_b32_e32 v73, v0
	v_mov_b32_e32 v74, v0
	v_mov_b32_e32 v75, v0
	v_mov_b32_e32 v76, v0
	v_mov_b32_e32 v77, v0
	v_mov_b32_e32 v78, v0
	v_mov_b32_e32 v79, v0
	v_mov_b32_e32 v80, v0
	v_mov_b32_e32 v81, v0
	v_mov_b32_e32 v82, v0
	v_mov_b32_e32 v83, v0
	v_mov_b32_e32 v84, v0
	v_mov_b32_e32 v85, v0
	v_mov_b32_e32 v86, v0
	v_mov_b32_e32 v87, v0
	v_mov_b32_e32 v88, v0
	v_mov_b32_e32 v89, v0
	v_mov_b32_e32 v90, v0
	v_mov_b32_e32 v91, v0
	v_mov_b32_e32 v92, v0
	v_mov_b32_e32 v93, v0
	v_mov_b32_e32 v94, v0
	v_mov_b32_e32 v95, v0
	v_mov_b32_e32 v32, v0
	v_mov_b32_e32 v33, v0
	v_mov_b32_e32 v34, v0
	v_mov_b32_e32 v35, v0
	v_mov_b32_e32 v36, v0
	v_mov_b32_e32 v37, v0
	v_mov_b32_e32 v38, v0
	v_mov_b32_e32 v39, v0
	v_mov_b32_e32 v40, v0
	v_mov_b32_e32 v41, v0
	v_mov_b32_e32 v42, v0
	v_mov_b32_e32 v43, v0
	v_mov_b32_e32 v44, v0
	v_mov_b32_e32 v45, v0
	v_mov_b32_e32 v46, v0
	v_mov_b32_e32 v47, v0
	v_mov_b32_e32 v48, v0
	v_mov_b32_e32 v49, v0
	v_mov_b32_e32 v50, v0
	v_mov_b32_e32 v51, v0
	v_mov_b32_e32 v52, v0
	v_mov_b32_e32 v53, v0
	v_mov_b32_e32 v54, v0
	v_mov_b32_e32 v55, v0
	v_mov_b32_e32 v64, v0
	v_mov_b32_e32 v65, v0
	v_mov_b32_e32 v66, v0
	v_mov_b32_e32 v67, v0
	v_mov_b32_e32 v68, v0
	v_mov_b32_e32 v69, v0
	v_mov_b32_e32 v70, v0
	v_mov_b32_e32 v71, v0
	v_mov_b32_e32 v96, v0
	v_mov_b32_e32 v97, v0
	v_mov_b32_e32 v98, v0
	v_mov_b32_e32 v99, v0
	v_mov_b32_e32 v100, v0
	v_mov_b32_e32 v101, v0
	v_mov_b32_e32 v102, v0
	v_mov_b32_e32 v103, v0
	v_mov_b32_e32 v104, v0
	v_mov_b32_e32 v105, v0
	v_mov_b32_e32 v106, v0
	v_mov_b32_e32 v107, v0
	v_mov_b32_e32 v108, v0
	v_mov_b32_e32 v109, v0
	v_mov_b32_e32 v110, v0
	v_mov_b32_e32 v111, v0
	v_mov_b32_e32 v112, v0
	v_mov_b32_e32 v113, v0
	v_mov_b32_e32 v114, v0
	v_mov_b32_e32 v115, v0
	v_mov_b32_e32 v116, v0
	v_mov_b32_e32 v117, v0
	v_mov_b32_e32 v118, v0
	v_mov_b32_e32 v119, v0
	v_mov_b32_e32 v120, v0
	v_mov_b32_e32 v121, v0
	v_mov_b32_e32 v122, v0
	v_mov_b32_e32 v123, v0
	v_mov_b32_e32 v124, v0
	v_mov_b32_e32 v125, v0
	v_mov_b32_e32 v126, v0
	v_mov_b32_e32 v127, v0
	s_cmp_lg_u64 s[40:41], 0
	s_cbranch_scc1 .Lx_loop
.LBB0_277:
	s_add_u32 s10, s8, 0xfffc0080
	s_addc_u32 s11, s9, -1
	s_add_i32 s53, 16, 0x10000
	s_cmp_eq_u32 s52, 12
	s_cselect_b32 s13, s34, s11
	s_cselect_b32 s12, s35, s10
	s_cselect_b32 s11, s43, s51
	s_cselect_b32 s10, s45, s50
	s_add_i32 s56, 16, 0x14000
	v_add_u32_e32 v140, s53, v204
	v_add_u32_e32 v156, s56, v204
	ds_read_b128 v[128:131], v140
	ds_read_b128 v[132:135], v140 offset:1024
	ds_read_b128 v[136:139], v140 offset:2048
	ds_read_b128 v[140:143], v140 offset:3072
	ds_read_b128 v[144:147], v156
	ds_read_b128 v[176:179], v156 offset:1024
	ds_read_b128 v[208:211], v156 offset:2048
	ds_read_b128 v[212:215], v156 offset:3072
	v_lshl_add_u64 v[180:181], s[8:9], 0, v[172:173]
	s_add_i32 m0, s17, 0xc000
	ds_read_b128 v[216:219], v206
	ds_read_b128 v[220:223], v206 offset:1024
	ds_read_b128 v[224:227], v206 offset:2048
	ds_read_b128 v[228:231], v206 offset:3072
	ds_read_b128 v[232:235], v206 offset:4096
	ds_read_b128 v[236:239], v206 offset:5120
	ds_read_b128 v[240:243], v206 offset:6144
	ds_read_b128 v[244:247], v206 offset:7168
	global_load_lds_dwordx4 v[180:181], off
	v_lshl_add_u64 v[180:181], s[8:9], 0, v[174:175]
	s_add_i32 m0, s17, 0xe000
	s_nop 0
	global_load_lds_dwordx4 v[180:181], off
	s_waitcnt vmcnt(8)
	s_waitcnt lgkmcnt(0)
	s_barrier
	s_setprio 1
	s_waitcnt lgkmcnt(0)
	v_mfma_f32_16x16x32_bf16 v[124:127], v[128:131], v[216:219], v[124:127]
	v_mfma_f32_16x16x32_bf16 v[120:123], v[136:139], v[216:219], v[120:123]
	v_mfma_f32_16x16x32_bf16 v[116:119], v[128:131], v[224:227], v[116:119]
	v_mfma_f32_16x16x32_bf16 v[112:115], v[136:139], v[224:227], v[112:115]
	v_mfma_f32_16x16x32_bf16 v[108:111], v[128:131], v[232:235], v[108:111]
	v_mfma_f32_16x16x32_bf16 v[104:107], v[136:139], v[232:235], v[104:107]
	v_mfma_f32_16x16x32_bf16 v[100:103], v[128:131], v[240:243], v[100:103]
	v_mfma_f32_16x16x32_bf16 v[96:99], v[136:139], v[240:243], v[96:99]
	v_mfma_f32_16x16x32_bf16 v[124:127], v[132:135], v[220:223], v[124:127]
	v_mfma_f32_16x16x32_bf16 v[120:123], v[140:143], v[220:223], v[120:123]
	v_mfma_f32_16x16x32_bf16 v[116:119], v[132:135], v[228:231], v[116:119]
	v_mfma_f32_16x16x32_bf16 v[112:115], v[140:143], v[228:231], v[112:115]
	v_mfma_f32_16x16x32_bf16 v[108:111], v[132:135], v[236:239], v[108:111]
	v_mfma_f32_16x16x32_bf16 v[104:107], v[140:143], v[236:239], v[104:107]
	v_mfma_f32_16x16x32_bf16 v[100:103], v[132:135], v[244:247], v[100:103]
	v_mfma_f32_16x16x32_bf16 v[96:99], v[140:143], v[244:247], v[96:99]
	s_setprio 0
	s_setprio 1
	v_mfma_f32_16x16x32_bf16 v[68:71], v[144:147], v[216:219], v[68:71]
	v_mfma_f32_16x16x32_bf16 v[64:67], v[208:211], v[216:219], v[64:67]
	v_mfma_f32_16x16x32_bf16 v[52:55], v[144:147], v[224:227], v[52:55]
	v_mfma_f32_16x16x32_bf16 v[48:51], v[208:211], v[224:227], v[48:51]
	v_mfma_f32_16x16x32_bf16 v[44:47], v[144:147], v[232:235], v[44:47]
	v_mfma_f32_16x16x32_bf16 v[40:43], v[208:211], v[232:235], v[40:43]
	v_mfma_f32_16x16x32_bf16 v[36:39], v[144:147], v[240:243], v[36:39]
	v_mfma_f32_16x16x32_bf16 v[32:35], v[208:211], v[240:243], v[32:35]
	v_mfma_f32_16x16x32_bf16 v[68:71], v[176:179], v[220:223], v[68:71]
	v_mfma_f32_16x16x32_bf16 v[64:67], v[212:215], v[220:223], v[64:67]
	v_mfma_f32_16x16x32_bf16 v[52:55], v[176:179], v[228:231], v[52:55]
	v_mfma_f32_16x16x32_bf16 v[48:51], v[212:215], v[228:231], v[48:51]
	v_mfma_f32_16x16x32_bf16 v[44:47], v[176:179], v[236:239], v[44:47]
	v_mfma_f32_16x16x32_bf16 v[40:43], v[212:215], v[236:239], v[40:43]
	v_mfma_f32_16x16x32_bf16 v[36:39], v[176:179], v[244:247], v[36:39]
	v_mfma_f32_16x16x32_bf16 v[32:35], v[212:215], v[244:247], v[32:35]
	s_setprio 0
	s_barrier
	s_add_i32 s53, s53, s16
	v_lshl_add_u64 v[180:181], s[10:11], 0, v[152:153]
	s_mov_b32 m0, s53
	ds_read_b128 v[216:219], v206 offset:16384
	ds_read_b128 v[220:223], v206 offset:17408
	ds_read_b128 v[224:227], v206 offset:18432
	ds_read_b128 v[228:231], v206 offset:19456
	ds_read_b128 v[232:235], v206 offset:20480
	ds_read_b128 v[236:239], v206 offset:21504
	ds_read_b128 v[240:243], v206 offset:22528
	ds_read_b128 v[244:247], v206 offset:23552
	global_load_lds_dwordx4 v[180:181], off
	s_add_i32 m0, s53, 0x2000
	s_add_u32 s54, s10, 0x40000
	v_lshl_add_u64 v[248:249], s[10:11], 0, v[148:149]
	s_addc_u32 s55, s11, 0
	s_add_i32 s53, s56, s16
	global_load_lds_dwordx4 v[248:249], off
	v_lshl_add_u64 v[192:193], s[54:55], 0, v[152:153]
	s_mov_b32 m0, s53
	v_lshl_add_u64 v[158:159], s[12:13], 0, v[150:151]
	global_load_lds_dwordx4 v[192:193], off
	v_lshl_add_u64 v[192:193], s[54:55], 0, v[148:149]
	s_add_i32 m0, s53, 0x2000
	s_nop 0
	global_load_lds_dwordx4 v[192:193], off
	v_lshl_add_u64 v[192:193], s[12:13], 0, v[154:155]
	s_mov_b32 m0, s17
	s_nop 0
	global_load_lds_dwordx4 v[192:193], off
	s_mov_b32 m0, s18
	s_nop 0
	global_load_lds_dwordx4 v[158:159], off
	s_waitcnt vmcnt(8)
	s_waitcnt lgkmcnt(0)
	s_barrier
	s_setprio 1
	s_waitcnt lgkmcnt(0)
	v_mfma_f32_16x16x32_bf16 v[92:95], v[128:131], v[216:219], v[92:95]
	v_mfma_f32_16x16x32_bf16 v[88:91], v[136:139], v[216:219], v[88:91]
	v_mfma_f32_16x16x32_bf16 v[84:87], v[128:131], v[224:227], v[84:87]
	v_mfma_f32_16x16x32_bf16 v[80:83], v[136:139], v[224:227], v[80:83]
	v_mfma_f32_16x16x32_bf16 v[76:79], v[128:131], v[232:235], v[76:79]
	v_mfma_f32_16x16x32_bf16 v[72:75], v[136:139], v[232:235], v[72:75]
	v_mfma_f32_16x16x32_bf16 v[60:63], v[128:131], v[240:243], v[60:63]
	v_mfma_f32_16x16x32_bf16 v[56:59], v[136:139], v[240:243], v[56:59]
	v_mfma_f32_16x16x32_bf16 v[92:95], v[132:135], v[220:223], v[92:95]
	v_mfma_f32_16x16x32_bf16 v[88:91], v[140:143], v[220:223], v[88:91]
	v_mfma_f32_16x16x32_bf16 v[84:87], v[132:135], v[228:231], v[84:87]
	v_mfma_f32_16x16x32_bf16 v[80:83], v[140:143], v[228:231], v[80:83]
	v_mfma_f32_16x16x32_bf16 v[76:79], v[132:135], v[236:239], v[76:79]
	v_mfma_f32_16x16x32_bf16 v[72:75], v[140:143], v[236:239], v[72:75]
	v_mfma_f32_16x16x32_bf16 v[60:63], v[132:135], v[244:247], v[60:63]
	v_mfma_f32_16x16x32_bf16 v[56:59], v[140:143], v[244:247], v[56:59]
	s_setprio 0
	s_setprio 1
	v_mfma_f32_16x16x32_bf16 v[28:31], v[144:147], v[216:219], v[28:31]
	v_mfma_f32_16x16x32_bf16 v[24:27], v[208:211], v[216:219], v[24:27]
	v_mfma_f32_16x16x32_bf16 v[20:23], v[144:147], v[224:227], v[20:23]
	v_mfma_f32_16x16x32_bf16 v[16:19], v[208:211], v[224:227], v[16:19]
	v_mfma_f32_16x16x32_bf16 v[12:15], v[144:147], v[232:235], v[12:15]
	v_mfma_f32_16x16x32_bf16 v[8:11], v[208:211], v[232:235], v[8:11]
	v_mfma_f32_16x16x32_bf16 v[4:7], v[144:147], v[240:243], v[4:7]
	v_mfma_f32_16x16x32_bf16 v[0:3], v[208:211], v[240:243], v[0:3]
	v_mfma_f32_16x16x32_bf16 v[28:31], v[176:179], v[220:223], v[28:31]
	v_mfma_f32_16x16x32_bf16 v[24:27], v[212:215], v[220:223], v[24:27]
	v_mfma_f32_16x16x32_bf16 v[20:23], v[176:179], v[228:231], v[20:23]
	v_mfma_f32_16x16x32_bf16 v[16:19], v[212:215], v[228:231], v[16:19]
	v_mfma_f32_16x16x32_bf16 v[12:15], v[176:179], v[236:239], v[12:15]
	v_mfma_f32_16x16x32_bf16 v[8:11], v[212:215], v[236:239], v[8:11]
	v_mfma_f32_16x16x32_bf16 v[4:7], v[176:179], v[244:247], v[4:7]
	v_mfma_f32_16x16x32_bf16 v[0:3], v[212:215], v[244:247], v[0:3]
	s_setprio 0
	s_barrier
	s_add_i32 s53, 16, 0x18000
	s_add_i32 s54, 16, 0x1c000
	v_add_u32_e32 v140, s53, v204
	v_add_u32_e32 v156, s54, v204
	ds_read_b128 v[128:131], v140
	ds_read_b128 v[132:135], v140 offset:1024
	ds_read_b128 v[136:139], v140 offset:2048
	ds_read_b128 v[140:143], v140 offset:3072
	ds_read_b128 v[144:147], v156
	ds_read_b128 v[176:179], v156 offset:1024
	ds_read_b128 v[208:211], v156 offset:2048
	ds_read_b128 v[212:215], v156 offset:3072
	s_add_u32 s12, s12, 0x40000
	s_addc_u32 s13, s13, 0
	s_mov_b32 m0, s19
	v_lshl_add_u64 v[160:161], s[12:13], 0, v[154:155]
	ds_read_b128 v[216:219], v206 offset:32768
	ds_read_b128 v[220:223], v206 offset:33792
	ds_read_b128 v[224:227], v206 offset:34816
	ds_read_b128 v[228:231], v206 offset:35840
	ds_read_b128 v[232:235], v206 offset:36864
	ds_read_b128 v[236:239], v206 offset:37888
	ds_read_b128 v[240:243], v206 offset:38912
	ds_read_b128 v[244:247], v206 offset:39936
	global_load_lds_dwordx4 v[160:161], off
	v_lshl_add_u64 v[160:161], s[12:13], 0, v[150:151]
	s_mov_b32 m0, s20
	s_nop 0
	global_load_lds_dwordx4 v[160:161], off
	s_waitcnt vmcnt(8)
	s_waitcnt lgkmcnt(0)
	s_barrier
	s_setprio 1
	s_waitcnt lgkmcnt(0)
	v_mfma_f32_16x16x32_bf16 v[124:127], v[128:131], v[216:219], v[124:127]
	v_mfma_f32_16x16x32_bf16 v[120:123], v[136:139], v[216:219], v[120:123]
	v_mfma_f32_16x16x32_bf16 v[116:119], v[128:131], v[224:227], v[116:119]
	v_mfma_f32_16x16x32_bf16 v[112:115], v[136:139], v[224:227], v[112:115]
	v_mfma_f32_16x16x32_bf16 v[108:111], v[128:131], v[232:235], v[108:111]
	v_mfma_f32_16x16x32_bf16 v[104:107], v[136:139], v[232:235], v[104:107]
	v_mfma_f32_16x16x32_bf16 v[100:103], v[128:131], v[240:243], v[100:103]
	v_mfma_f32_16x16x32_bf16 v[96:99], v[136:139], v[240:243], v[96:99]
	v_mfma_f32_16x16x32_bf16 v[124:127], v[132:135], v[220:223], v[124:127]
	v_mfma_f32_16x16x32_bf16 v[120:123], v[140:143], v[220:223], v[120:123]
	v_mfma_f32_16x16x32_bf16 v[116:119], v[132:135], v[228:231], v[116:119]
	v_mfma_f32_16x16x32_bf16 v[112:115], v[140:143], v[228:231], v[112:115]
	v_mfma_f32_16x16x32_bf16 v[108:111], v[132:135], v[236:239], v[108:111]
	v_mfma_f32_16x16x32_bf16 v[104:107], v[140:143], v[236:239], v[104:107]
	v_mfma_f32_16x16x32_bf16 v[100:103], v[132:135], v[244:247], v[100:103]
	v_mfma_f32_16x16x32_bf16 v[96:99], v[140:143], v[244:247], v[96:99]
	s_setprio 0
	s_setprio 1
	v_mfma_f32_16x16x32_bf16 v[68:71], v[144:147], v[216:219], v[68:71]
	v_mfma_f32_16x16x32_bf16 v[64:67], v[208:211], v[216:219], v[64:67]
	v_mfma_f32_16x16x32_bf16 v[52:55], v[144:147], v[224:227], v[52:55]
	v_mfma_f32_16x16x32_bf16 v[48:51], v[208:211], v[224:227], v[48:51]
	v_mfma_f32_16x16x32_bf16 v[44:47], v[144:147], v[232:235], v[44:47]
	v_mfma_f32_16x16x32_bf16 v[40:43], v[208:211], v[232:235], v[40:43]
	v_mfma_f32_16x16x32_bf16 v[36:39], v[144:147], v[240:243], v[36:39]
	v_mfma_f32_16x16x32_bf16 v[32:35], v[208:211], v[240:243], v[32:35]
	v_mfma_f32_16x16x32_bf16 v[68:71], v[176:179], v[220:223], v[68:71]
	v_mfma_f32_16x16x32_bf16 v[64:67], v[212:215], v[220:223], v[64:67]
	v_mfma_f32_16x16x32_bf16 v[52:55], v[176:179], v[228:231], v[52:55]
	v_mfma_f32_16x16x32_bf16 v[48:51], v[212:215], v[228:231], v[48:51]
	v_mfma_f32_16x16x32_bf16 v[44:47], v[176:179], v[236:239], v[44:47]
	v_mfma_f32_16x16x32_bf16 v[40:43], v[212:215], v[236:239], v[40:43]
	v_mfma_f32_16x16x32_bf16 v[36:39], v[176:179], v[244:247], v[36:39]
	v_mfma_f32_16x16x32_bf16 v[32:35], v[212:215], v[244:247], v[32:35]
	s_setprio 0
	s_barrier
	s_add_i32 s12, s53, s16
	v_lshl_add_u64 v[160:161], v[180:181], 0, s[30:31]
	s_mov_b32 m0, s12
	ds_read_b128 v[216:219], v206 offset:49152
	ds_read_b128 v[220:223], v206 offset:50176
	ds_read_b128 v[224:227], v206 offset:51200
	ds_read_b128 v[228:231], v206 offset:52224
	ds_read_b128 v[232:235], v206 offset:53248
	ds_read_b128 v[236:239], v206 offset:54272
	ds_read_b128 v[240:243], v206 offset:55296
	ds_read_b128 v[244:247], v206 offset:56320
	global_load_lds_dwordx4 v[160:161], off
	s_add_i32 m0, s12, 0x2000
	s_add_u32 s10, s10, 0x40080
	v_lshl_add_u64 v[160:161], v[248:249], 0, s[30:31]
	s_addc_u32 s11, s11, 0
	s_add_i32 s12, s54, s16
	global_load_lds_dwordx4 v[160:161], off
	v_lshl_add_u64 v[160:161], s[10:11], 0, v[152:153]
	s_mov_b32 m0, s12
	v_lshl_add_u64 v[158:159], v[158:159], 0, s[30:31]
	global_load_lds_dwordx4 v[160:161], off
	v_lshl_add_u64 v[160:161], s[10:11], 0, v[148:149]
	s_add_i32 m0, s12, 0x2000
	s_nop 0
	global_load_lds_dwordx4 v[160:161], off
	v_lshl_add_u64 v[160:161], v[192:193], 0, s[30:31]
	s_mov_b32 m0, s21
	s_nop 0
	global_load_lds_dwordx4 v[160:161], off
	s_mov_b32 m0, s22
	s_nop 0
	global_load_lds_dwordx4 v[158:159], off
	s_waitcnt vmcnt(8)
	s_waitcnt lgkmcnt(0)
	s_barrier
	s_setprio 1
	s_waitcnt lgkmcnt(0)
	v_mfma_f32_16x16x32_bf16 v[92:95], v[128:131], v[216:219], v[92:95]
	v_mfma_f32_16x16x32_bf16 v[88:91], v[136:139], v[216:219], v[88:91]
	v_mfma_f32_16x16x32_bf16 v[84:87], v[128:131], v[224:227], v[84:87]
	v_mfma_f32_16x16x32_bf16 v[80:83], v[136:139], v[224:227], v[80:83]
	v_mfma_f32_16x16x32_bf16 v[76:79], v[128:131], v[232:235], v[76:79]
	v_mfma_f32_16x16x32_bf16 v[72:75], v[136:139], v[232:235], v[72:75]
	v_mfma_f32_16x16x32_bf16 v[60:63], v[128:131], v[240:243], v[60:63]
	v_mfma_f32_16x16x32_bf16 v[56:59], v[136:139], v[240:243], v[56:59]
	v_mfma_f32_16x16x32_bf16 v[92:95], v[132:135], v[220:223], v[92:95]
	v_mfma_f32_16x16x32_bf16 v[88:91], v[140:143], v[220:223], v[88:91]
	v_mfma_f32_16x16x32_bf16 v[84:87], v[132:135], v[228:231], v[84:87]
	v_mfma_f32_16x16x32_bf16 v[80:83], v[140:143], v[228:231], v[80:83]
	v_mfma_f32_16x16x32_bf16 v[76:79], v[132:135], v[236:239], v[76:79]
	v_mfma_f32_16x16x32_bf16 v[72:75], v[140:143], v[236:239], v[72:75]
	v_mfma_f32_16x16x32_bf16 v[60:63], v[132:135], v[244:247], v[60:63]
	v_mfma_f32_16x16x32_bf16 v[56:59], v[140:143], v[244:247], v[56:59]
	s_setprio 0
	s_setprio 1
	v_mfma_f32_16x16x32_bf16 v[28:31], v[144:147], v[216:219], v[28:31]
	v_mfma_f32_16x16x32_bf16 v[24:27], v[208:211], v[216:219], v[24:27]
	v_mfma_f32_16x16x32_bf16 v[20:23], v[144:147], v[224:227], v[20:23]
	v_mfma_f32_16x16x32_bf16 v[16:19], v[208:211], v[224:227], v[16:19]
	v_mfma_f32_16x16x32_bf16 v[12:15], v[144:147], v[232:235], v[12:15]
	v_mfma_f32_16x16x32_bf16 v[8:11], v[208:211], v[232:235], v[8:11]
	v_mfma_f32_16x16x32_bf16 v[4:7], v[144:147], v[240:243], v[4:7]
	v_mfma_f32_16x16x32_bf16 v[0:3], v[208:211], v[240:243], v[0:3]
	v_mfma_f32_16x16x32_bf16 v[28:31], v[176:179], v[220:223], v[28:31]
	v_mfma_f32_16x16x32_bf16 v[24:27], v[212:215], v[220:223], v[24:27]
	v_mfma_f32_16x16x32_bf16 v[20:23], v[176:179], v[228:231], v[20:23]
	v_mfma_f32_16x16x32_bf16 v[16:19], v[212:215], v[228:231], v[16:19]
	v_mfma_f32_16x16x32_bf16 v[12:15], v[176:179], v[236:239], v[12:15]
	v_mfma_f32_16x16x32_bf16 v[8:11], v[212:215], v[236:239], v[8:11]
	v_mfma_f32_16x16x32_bf16 v[4:7], v[176:179], v[244:247], v[4:7]
	v_mfma_f32_16x16x32_bf16 v[0:3], v[212:215], v[244:247], v[0:3]
	s_setprio 0
	s_barrier
	s_add_i32 s52, s52, 2
	s_add_u32 s8, s8, 0x100
	s_addc_u32 s9, s9, 0
	s_add_u32 s50, s50, 0x100
	s_addc_u32 s51, s51, 0
	s_cmp_gt_u32 s52, 13
	s_cbranch_scc0 .LBB0_277
	s_branch .Lpost_loop
.Lx_loop:
	s_add_u32 s10, s8, 0xfffc0080
	s_addc_u32 s11, s9, -1
	s_add_i32 s53, 16, 0x10000
	s_cmp_eq_u32 s52, 12
	s_cselect_b32 s13, s34, s11
	s_cselect_b32 s12, s35, s10
	s_cselect_b32 s11, s43, s51
	s_cselect_b32 s10, s45, s50
	s_add_i32 s56, 16, 0x14000
	v_add_u32_e32 v140, s53, v204
	v_add_u32_e32 v156, s56, v204
	ds_read_b128 v[128:131], v140
	ds_read_b128 v[132:135], v140 offset:1024
	ds_read_b128 v[136:139], v140 offset:2048
	ds_read_b128 v[140:143], v140 offset:3072
	ds_read_b128 v[144:147], v156
	ds_read_b128 v[176:179], v156 offset:1024
	ds_read_b128 v[208:211], v156 offset:2048
	ds_read_b128 v[212:215], v156 offset:3072
	v_lshl_add_u64 v[180:181], s[8:9], 0, v[172:173]
	s_add_i32 m0, s17, 0xc000
	ds_read_b128 v[216:219], v206
	ds_read_b128 v[220:223], v206 offset:1024
	ds_read_b128 v[224:227], v206 offset:2048
	ds_read_b128 v[228:231], v206 offset:3072
	ds_read_b128 v[232:235], v206 offset:4096
	ds_read_b128 v[236:239], v206 offset:5120
	ds_read_b128 v[240:243], v206 offset:6144
	ds_read_b128 v[244:247], v206 offset:7168
	global_load_lds_dwordx4 v[180:181], off
	v_lshl_add_u64 v[180:181], s[8:9], 0, v[174:175]
	s_add_i32 m0, s17, 0xe000
	s_nop 0
	global_load_lds_dwordx4 v[180:181], off
	s_waitcnt lgkmcnt(0)
	s_barrier
	s_setprio 1
	s_waitcnt lgkmcnt(0)
	v_mfma_f32_16x16x32_bf16 v[124:127], v[128:131], v[216:219], v[124:127]
	v_mfma_f32_16x16x32_bf16 v[120:123], v[136:139], v[216:219], v[120:123]
	v_mfma_f32_16x16x32_bf16 v[116:119], v[128:131], v[224:227], v[116:119]
	v_mfma_f32_16x16x32_bf16 v[112:115], v[136:139], v[224:227], v[112:115]
	v_mfma_f32_16x16x32_bf16 v[108:111], v[128:131], v[232:235], v[108:111]
	v_mfma_f32_16x16x32_bf16 v[104:107], v[136:139], v[232:235], v[104:107]
	v_mfma_f32_16x16x32_bf16 v[100:103], v[128:131], v[240:243], v[100:103]
	v_mfma_f32_16x16x32_bf16 v[96:99], v[136:139], v[240:243], v[96:99]
	v_mfma_f32_16x16x32_bf16 v[124:127], v[132:135], v[220:223], v[124:127]
	v_mfma_f32_16x16x32_bf16 v[120:123], v[140:143], v[220:223], v[120:123]
	v_mfma_f32_16x16x32_bf16 v[116:119], v[132:135], v[228:231], v[116:119]
	v_mfma_f32_16x16x32_bf16 v[112:115], v[140:143], v[228:231], v[112:115]
	v_mfma_f32_16x16x32_bf16 v[108:111], v[132:135], v[236:239], v[108:111]
	v_mfma_f32_16x16x32_bf16 v[104:107], v[140:143], v[236:239], v[104:107]
	v_mfma_f32_16x16x32_bf16 v[100:103], v[132:135], v[244:247], v[100:103]
	v_mfma_f32_16x16x32_bf16 v[96:99], v[140:143], v[244:247], v[96:99]
	s_setprio 0
	s_setprio 1
	v_mfma_f32_16x16x32_bf16 v[68:71], v[144:147], v[216:219], v[68:71]
	v_mfma_f32_16x16x32_bf16 v[64:67], v[208:211], v[216:219], v[64:67]
	v_mfma_f32_16x16x32_bf16 v[52:55], v[144:147], v[224:227], v[52:55]
	v_mfma_f32_16x16x32_bf16 v[48:51], v[208:211], v[224:227], v[48:51]
	v_mfma_f32_16x16x32_bf16 v[44:47], v[144:147], v[232:235], v[44:47]
	v_mfma_f32_16x16x32_bf16 v[40:43], v[208:211], v[232:235], v[40:43]
	v_mfma_f32_16x16x32_bf16 v[36:39], v[144:147], v[240:243], v[36:39]
	v_mfma_f32_16x16x32_bf16 v[32:35], v[208:211], v[240:243], v[32:35]
	v_mfma_f32_16x16x32_bf16 v[68:71], v[176:179], v[220:223], v[68:71]
	v_mfma_f32_16x16x32_bf16 v[64:67], v[212:215], v[220:223], v[64:67]
	v_mfma_f32_16x16x32_bf16 v[52:55], v[176:179], v[228:231], v[52:55]
	v_mfma_f32_16x16x32_bf16 v[48:51], v[212:215], v[228:231], v[48:51]
	v_mfma_f32_16x16x32_bf16 v[44:47], v[176:179], v[236:239], v[44:47]
	v_mfma_f32_16x16x32_bf16 v[40:43], v[212:215], v[236:239], v[40:43]
	v_mfma_f32_16x16x32_bf16 v[36:39], v[176:179], v[244:247], v[36:39]
	v_mfma_f32_16x16x32_bf16 v[32:35], v[212:215], v[244:247], v[32:35]
	s_setprio 0
	s_waitcnt vmcnt(8)
	s_barrier
	s_add_i32 s53, s53, s16
	v_lshl_add_u64 v[180:181], s[10:11], 0, v[152:153]
	s_mov_b32 m0, s53
	ds_read_b128 v[216:219], v206 offset:16384
	ds_read_b128 v[220:223], v206 offset:17408
	ds_read_b128 v[224:227], v206 offset:18432
	ds_read_b128 v[228:231], v206 offset:19456
	ds_read_b128 v[232:235], v206 offset:20480
	ds_read_b128 v[236:239], v206 offset:21504
	ds_read_b128 v[240:243], v206 offset:22528
	ds_read_b128 v[244:247], v206 offset:23552
	global_load_lds_dwordx4 v[180:181], off
	s_add_i32 m0, s53, 0x2000
	s_add_u32 s54, s10, 0x40000
	v_lshl_add_u64 v[248:249], s[10:11], 0, v[148:149]
	s_addc_u32 s55, s11, 0
	s_add_i32 s53, s56, s16
	global_load_lds_dwordx4 v[248:249], off
	v_lshl_add_u64 v[192:193], s[54:55], 0, v[152:153]
	s_mov_b32 m0, s53
	v_lshl_add_u64 v[158:159], s[12:13], 0, v[150:151]
	global_load_lds_dwordx4 v[192:193], off
	v_lshl_add_u64 v[192:193], s[54:55], 0, v[148:149]
	s_add_i32 m0, s53, 0x2000
	s_nop 0
	global_load_lds_dwordx4 v[192:193], off
	v_lshl_add_u64 v[192:193], s[12:13], 0, v[154:155]
	s_mov_b32 m0, s17
	s_nop 0
	global_load_lds_dwordx4 v[192:193], off
	s_mov_b32 m0, s18
	s_nop 0
	global_load_lds_dwordx4 v[158:159], off
	s_waitcnt lgkmcnt(0)
	s_barrier
	s_setprio 1
	s_waitcnt lgkmcnt(0)
	v_mfma_f32_16x16x32_bf16 v[92:95], v[128:131], v[216:219], v[92:95]
	v_mfma_f32_16x16x32_bf16 v[88:91], v[136:139], v[216:219], v[88:91]
	v_mfma_f32_16x16x32_bf16 v[84:87], v[128:131], v[224:227], v[84:87]
	v_mfma_f32_16x16x32_bf16 v[80:83], v[136:139], v[224:227], v[80:83]
	v_mfma_f32_16x16x32_bf16 v[76:79], v[128:131], v[232:235], v[76:79]
	v_mfma_f32_16x16x32_bf16 v[72:75], v[136:139], v[232:235], v[72:75]
	v_mfma_f32_16x16x32_bf16 v[60:63], v[128:131], v[240:243], v[60:63]
	v_mfma_f32_16x16x32_bf16 v[56:59], v[136:139], v[240:243], v[56:59]
	v_mfma_f32_16x16x32_bf16 v[92:95], v[132:135], v[220:223], v[92:95]
	v_mfma_f32_16x16x32_bf16 v[88:91], v[140:143], v[220:223], v[88:91]
	v_mfma_f32_16x16x32_bf16 v[84:87], v[132:135], v[228:231], v[84:87]
	v_mfma_f32_16x16x32_bf16 v[80:83], v[140:143], v[228:231], v[80:83]
	v_mfma_f32_16x16x32_bf16 v[76:79], v[132:135], v[236:239], v[76:79]
	v_mfma_f32_16x16x32_bf16 v[72:75], v[140:143], v[236:239], v[72:75]
	v_mfma_f32_16x16x32_bf16 v[60:63], v[132:135], v[244:247], v[60:63]
	v_mfma_f32_16x16x32_bf16 v[56:59], v[140:143], v[244:247], v[56:59]
	s_setprio 0
	s_setprio 1
	v_mfma_f32_16x16x32_bf16 v[28:31], v[144:147], v[216:219], v[28:31]
	v_mfma_f32_16x16x32_bf16 v[24:27], v[208:211], v[216:219], v[24:27]
	v_mfma_f32_16x16x32_bf16 v[20:23], v[144:147], v[224:227], v[20:23]
	v_mfma_f32_16x16x32_bf16 v[16:19], v[208:211], v[224:227], v[16:19]
	v_mfma_f32_16x16x32_bf16 v[12:15], v[144:147], v[232:235], v[12:15]
	v_mfma_f32_16x16x32_bf16 v[8:11], v[208:211], v[232:235], v[8:11]
	v_mfma_f32_16x16x32_bf16 v[4:7], v[144:147], v[240:243], v[4:7]
	v_mfma_f32_16x16x32_bf16 v[0:3], v[208:211], v[240:243], v[0:3]
	v_mfma_f32_16x16x32_bf16 v[28:31], v[176:179], v[220:223], v[28:31]
	v_mfma_f32_16x16x32_bf16 v[24:27], v[212:215], v[220:223], v[24:27]
	v_mfma_f32_16x16x32_bf16 v[20:23], v[176:179], v[228:231], v[20:23]
	v_mfma_f32_16x16x32_bf16 v[16:19], v[212:215], v[228:231], v[16:19]
	v_mfma_f32_16x16x32_bf16 v[12:15], v[176:179], v[236:239], v[12:15]
	v_mfma_f32_16x16x32_bf16 v[8:11], v[212:215], v[236:239], v[8:11]
	v_mfma_f32_16x16x32_bf16 v[4:7], v[176:179], v[244:247], v[4:7]
	v_mfma_f32_16x16x32_bf16 v[0:3], v[212:215], v[244:247], v[0:3]
	s_setprio 0
	s_waitcnt vmcnt(8)
	s_barrier
	s_add_i32 s53, 16, 0x18000
	s_add_i32 s54, 16, 0x1c000
	v_add_u32_e32 v140, s53, v204
	v_add_u32_e32 v156, s54, v204
	ds_read_b128 v[128:131], v140
	ds_read_b128 v[132:135], v140 offset:1024
	ds_read_b128 v[136:139], v140 offset:2048
	ds_read_b128 v[140:143], v140 offset:3072
	ds_read_b128 v[144:147], v156
	ds_read_b128 v[176:179], v156 offset:1024
	ds_read_b128 v[208:211], v156 offset:2048
	ds_read_b128 v[212:215], v156 offset:3072
	s_add_u32 s12, s12, 0x40000
	s_addc_u32 s13, s13, 0
	s_mov_b32 m0, s19
	v_lshl_add_u64 v[160:161], s[12:13], 0, v[154:155]
	ds_read_b128 v[216:219], v206 offset:32768
	ds_read_b128 v[220:223], v206 offset:33792
	ds_read_b128 v[224:227], v206 offset:34816
	ds_read_b128 v[228:231], v206 offset:35840
	ds_read_b128 v[232:235], v206 offset:36864
	ds_read_b128 v[236:239], v206 offset:37888
	ds_read_b128 v[240:243], v206 offset:38912
	ds_read_b128 v[244:247], v206 offset:39936
	global_load_lds_dwordx4 v[160:161], off
	v_lshl_add_u64 v[160:161], s[12:13], 0, v[150:151]
	s_mov_b32 m0, s20
	s_nop 0
	global_load_lds_dwordx4 v[160:161], off
	s_waitcnt lgkmcnt(0)
	s_barrier
	s_setprio 1
	s_waitcnt lgkmcnt(0)
	v_mfma_f32_16x16x32_bf16 v[124:127], v[128:131], v[216:219], v[124:127]
	v_mfma_f32_16x16x32_bf16 v[120:123], v[136:139], v[216:219], v[120:123]
	v_mfma_f32_16x16x32_bf16 v[116:119], v[128:131], v[224:227], v[116:119]
	v_mfma_f32_16x16x32_bf16 v[112:115], v[136:139], v[224:227], v[112:115]
	v_mfma_f32_16x16x32_bf16 v[108:111], v[128:131], v[232:235], v[108:111]
	v_mfma_f32_16x16x32_bf16 v[104:107], v[136:139], v[232:235], v[104:107]
	v_mfma_f32_16x16x32_bf16 v[100:103], v[128:131], v[240:243], v[100:103]
	v_mfma_f32_16x16x32_bf16 v[96:99], v[136:139], v[240:243], v[96:99]
	v_mfma_f32_16x16x32_bf16 v[124:127], v[132:135], v[220:223], v[124:127]
	v_mfma_f32_16x16x32_bf16 v[120:123], v[140:143], v[220:223], v[120:123]
	v_mfma_f32_16x16x32_bf16 v[116:119], v[132:135], v[228:231], v[116:119]
	v_mfma_f32_16x16x32_bf16 v[112:115], v[140:143], v[228:231], v[112:115]
	v_mfma_f32_16x16x32_bf16 v[108:111], v[132:135], v[236:239], v[108:111]
	v_mfma_f32_16x16x32_bf16 v[104:107], v[140:143], v[236:239], v[104:107]
	v_mfma_f32_16x16x32_bf16 v[100:103], v[132:135], v[244:247], v[100:103]
	v_mfma_f32_16x16x32_bf16 v[96:99], v[140:143], v[244:247], v[96:99]
	s_setprio 0
	s_setprio 1
	v_mfma_f32_16x16x32_bf16 v[68:71], v[144:147], v[216:219], v[68:71]
	v_mfma_f32_16x16x32_bf16 v[64:67], v[208:211], v[216:219], v[64:67]
	v_mfma_f32_16x16x32_bf16 v[52:55], v[144:147], v[224:227], v[52:55]
	v_mfma_f32_16x16x32_bf16 v[48:51], v[208:211], v[224:227], v[48:51]
	v_mfma_f32_16x16x32_bf16 v[44:47], v[144:147], v[232:235], v[44:47]
	v_mfma_f32_16x16x32_bf16 v[40:43], v[208:211], v[232:235], v[40:43]
	v_mfma_f32_16x16x32_bf16 v[36:39], v[144:147], v[240:243], v[36:39]
	v_mfma_f32_16x16x32_bf16 v[32:35], v[208:211], v[240:243], v[32:35]
	v_mfma_f32_16x16x32_bf16 v[68:71], v[176:179], v[220:223], v[68:71]
	v_mfma_f32_16x16x32_bf16 v[64:67], v[212:215], v[220:223], v[64:67]
	v_mfma_f32_16x16x32_bf16 v[52:55], v[176:179], v[228:231], v[52:55]
	v_mfma_f32_16x16x32_bf16 v[48:51], v[212:215], v[228:231], v[48:51]
	v_mfma_f32_16x16x32_bf16 v[44:47], v[176:179], v[236:239], v[44:47]
	v_mfma_f32_16x16x32_bf16 v[40:43], v[212:215], v[236:239], v[40:43]
	v_mfma_f32_16x16x32_bf16 v[36:39], v[176:179], v[244:247], v[36:39]
	v_mfma_f32_16x16x32_bf16 v[32:35], v[212:215], v[244:247], v[32:35]
	s_setprio 0
	s_waitcnt vmcnt(8)
	s_barrier
	s_add_i32 s12, s53, s16
	v_lshl_add_u64 v[160:161], v[180:181], 0, s[30:31]
	s_mov_b32 m0, s12
	ds_read_b128 v[216:219], v206 offset:49152
	ds_read_b128 v[220:223], v206 offset:50176
	ds_read_b128 v[224:227], v206 offset:51200
	ds_read_b128 v[228:231], v206 offset:52224
	ds_read_b128 v[232:235], v206 offset:53248
	ds_read_b128 v[236:239], v206 offset:54272
	ds_read_b128 v[240:243], v206 offset:55296
	ds_read_b128 v[244:247], v206 offset:56320
	global_load_lds_dwordx4 v[160:161], off
	s_add_i32 m0, s12, 0x2000
	s_add_u32 s10, s10, 0x40080
	v_lshl_add_u64 v[160:161], v[248:249], 0, s[30:31]
	s_addc_u32 s11, s11, 0
	s_add_i32 s12, s54, s16
	global_load_lds_dwordx4 v[160:161], off
	v_lshl_add_u64 v[160:161], s[10:11], 0, v[152:153]
	s_mov_b32 m0, s12
	v_lshl_add_u64 v[158:159], v[158:159], 0, s[30:31]
	global_load_lds_dwordx4 v[160:161], off
	v_lshl_add_u64 v[160:161], s[10:11], 0, v[148:149]
	s_add_i32 m0, s12, 0x2000
	s_nop 0
	global_load_lds_dwordx4 v[160:161], off
	v_lshl_add_u64 v[160:161], v[192:193], 0, s[30:31]
	s_mov_b32 m0, s21
	s_nop 0
	global_load_lds_dwordx4 v[160:161], off
	s_mov_b32 m0, s22
	s_nop 0
	global_load_lds_dwordx4 v[158:159], off
	s_waitcnt lgkmcnt(0)
	s_barrier
	s_setprio 1
	s_waitcnt lgkmcnt(0)
	v_mfma_f32_16x16x32_bf16 v[92:95], v[128:131], v[216:219], v[92:95]
	v_mfma_f32_16x16x32_bf16 v[88:91], v[136:139], v[216:219], v[88:91]
	v_mfma_f32_16x16x32_bf16 v[84:87], v[128:131], v[224:227], v[84:87]
	v_mfma_f32_16x16x32_bf16 v[80:83], v[136:139], v[224:227], v[80:83]
	v_mfma_f32_16x16x32_bf16 v[76:79], v[128:131], v[232:235], v[76:79]
	v_mfma_f32_16x16x32_bf16 v[72:75], v[136:139], v[232:235], v[72:75]
	v_mfma_f32_16x16x32_bf16 v[60:63], v[128:131], v[240:243], v[60:63]
	v_mfma_f32_16x16x32_bf16 v[56:59], v[136:139], v[240:243], v[56:59]
	v_mfma_f32_16x16x32_bf16 v[92:95], v[132:135], v[220:223], v[92:95]
	v_mfma_f32_16x16x32_bf16 v[88:91], v[140:143], v[220:223], v[88:91]
	v_mfma_f32_16x16x32_bf16 v[84:87], v[132:135], v[228:231], v[84:87]
	v_mfma_f32_16x16x32_bf16 v[80:83], v[140:143], v[228:231], v[80:83]
	v_mfma_f32_16x16x32_bf16 v[76:79], v[132:135], v[236:239], v[76:79]
	v_mfma_f32_16x16x32_bf16 v[72:75], v[140:143], v[236:239], v[72:75]
	v_mfma_f32_16x16x32_bf16 v[60:63], v[132:135], v[244:247], v[60:63]
	v_mfma_f32_16x16x32_bf16 v[56:59], v[140:143], v[244:247], v[56:59]
	s_setprio 0
	s_setprio 1
	v_mfma_f32_16x16x32_bf16 v[28:31], v[144:147], v[216:219], v[28:31]
	v_mfma_f32_16x16x32_bf16 v[24:27], v[208:211], v[216:219], v[24:27]
	v_mfma_f32_16x16x32_bf16 v[20:23], v[144:147], v[224:227], v[20:23]
	v_mfma_f32_16x16x32_bf16 v[16:19], v[208:211], v[224:227], v[16:19]
	v_mfma_f32_16x16x32_bf16 v[12:15], v[144:147], v[232:235], v[12:15]
	v_mfma_f32_16x16x32_bf16 v[8:11], v[208:211], v[232:235], v[8:11]
	v_mfma_f32_16x16x32_bf16 v[4:7], v[144:147], v[240:243], v[4:7]
	v_mfma_f32_16x16x32_bf16 v[0:3], v[208:211], v[240:243], v[0:3]
	v_mfma_f32_16x16x32_bf16 v[28:31], v[176:179], v[220:223], v[28:31]
	v_mfma_f32_16x16x32_bf16 v[24:27], v[212:215], v[220:223], v[24:27]
	v_mfma_f32_16x16x32_bf16 v[20:23], v[176:179], v[228:231], v[20:23]
	v_mfma_f32_16x16x32_bf16 v[16:19], v[212:215], v[228:231], v[16:19]
	v_mfma_f32_16x16x32_bf16 v[12:15], v[176:179], v[236:239], v[12:15]
	v_mfma_f32_16x16x32_bf16 v[8:11], v[212:215], v[236:239], v[8:11]
	v_mfma_f32_16x16x32_bf16 v[4:7], v[176:179], v[244:247], v[4:7]
	v_mfma_f32_16x16x32_bf16 v[0:3], v[212:215], v[244:247], v[0:3]
	s_setprio 0
	s_waitcnt vmcnt(8)
	s_barrier
	s_add_i32 s52, s52, 2
	s_add_u32 s8, s8, 0x100
	s_addc_u32 s9, s9, 0
	s_add_u32 s50, s50, 0x100
	s_addc_u32 s51, s51, 0
	s_cmp_gt_u32 s52, 13
	s_cbranch_scc0 .Lx_loop
.Lpost_loop:
	s_and_b64 vcc, exec, s[40:41]
	s_cbranch_vccz .LBB0_280
	s_barrier
